# v30 with all per-segment s_setprio removed and one static s_setprio 1 for waves 4-7 at kernel entry (strategy 6.3 recipe)
# baseline (speedup 1.0000x reference)
_Z3fwd4Args:
	s_load_dwordx2 s[74:75], s[0:1], 0xd8
	s_mov_b32 s76, s2
	v_readfirstlane_b32 s98, v0
	s_nop 3
	s_lshr_b32 s98, s98, 6
	s_cmp_ge_u32 s98, 4
	s_cbranch_scc0 .Lprio_done
	s_setprio 1
.Lprio_done:
	v_cmp_gt_u32_e64 s[6:7], 64, v0
	s_and_saveexec_b64 s[4:5], s[6:7]
	v_lshl_add_u32 v1, v0, 2, 0
	v_add_u32_e32 v1, 0x25f00, v1
	v_mov_b32_e32 v2, 0
	ds_write_b32 v1, v2
	s_or_b64 exec, exec, s[4:5]
	s_waitcnt lgkmcnt(0)
	s_barrier
	s_getreg_b32 s2, hwreg(HW_REG_XCC_ID, 0, 4)
	s_and_b32 s85, s2, 15
	v_cmp_eq_u32_e64 s[86:87], 0, v0
	s_and_saveexec_b64 s[4:5], s[86:87]
	s_cbranch_execz .LBB0_5
	s_mov_b64 s[8:9], exec
	v_mbcnt_lo_u32_b32 v1, s8, 0
	v_mbcnt_hi_u32_b32 v1, s9, v1
	v_cmp_eq_u32_e32 vcc, 0, v1
	s_and_b64 s[2:3], exec, vcc
	s_mov_b64 exec, s[2:3]
	s_cbranch_execz .LBB0_5
	s_lshl_b32 s2, s85, 8
	s_bcnt1_i32_b64 s3, s[8:9]
	v_mov_b32_e32 v1, s2
	v_mov_b32_e32 v2, s3
	global_atomic_add v1, v2, s[74:75] offset:1024
